# S5 pass-2 recurrence: VOP2 v_fmac_f32 (negated imaginary parts kept in two VGPRs) instead of VOP3 v_fma_f32
# baseline (speedup 1.0000x reference)
.LBB0_185:
	s_or_b64 exec, exec, s[2:3]
	s_lshl_b32 s24, s14, 2
	v_lshl_add_u64 v[0:1], v[160:161], 0, s[24:25]
	s_waitcnt vmcnt(0)
	global_load_dwordx4 v[96:99], v[0:1], off
	global_load_dwordx4 v[100:103], v[0:1], off offset:32
	s_lshl_b32 s2, s66, 7
	s_and_b32 s2, s2, 0xffffe000
	v_or3_b32 v120, s2, v197, v155
	v_ashrrev_i32_e32 v121, 31, v120
	v_lshl_add_u64 v[0:1], v[168:169], 0, v[120:121]
	v_lshl_add_u64 v[2:3], v[166:167], 0, v[120:121]
	v_lshl_add_u64 v[4:5], v[164:165], 0, v[120:121]
	v_lshl_add_u64 v[6:7], v[162:163], 0, v[120:121]
	v_cndmask_b32_e64 v1, v1, 0, s[10:11]
	v_cndmask_b32_e64 v0, v0, v154, s[10:11]
	v_cndmask_b32_e64 v3, v3, 0, s[8:9]
	v_cndmask_b32_e64 v2, v2, v154, s[8:9]
	v_cndmask_b32_e64 v5, v5, 0, s[6:7]
	v_cndmask_b32_e64 v4, v4, v154, s[6:7]
	v_cndmask_b32_e64 v7, v7, 0, s[4:5]
	v_cndmask_b32_e64 v6, v6, v154, s[4:5]
	v_lshlrev_b64 v[0:1], 11, v[0:1]
	v_mov_b32_e32 v185, v149
	v_lshlrev_b64 v[2:3], 11, v[2:3]
	v_lshlrev_b64 v[4:5], 11, v[4:5]
	v_lshlrev_b64 v[6:7], 11, v[6:7]
	v_lshl_add_u64 v[0:1], s[84:85], 0, v[0:1]
	v_lshl_add_u64 v[2:3], s[84:85], 0, v[2:3]
	v_lshl_add_u64 v[4:5], s[84:85], 0, v[4:5]
	v_lshl_add_u64 v[6:7], s[84:85], 0, v[6:7]
	v_lshl_add_u64 v[0:1], v[0:1], 0, v[184:185]
	v_lshl_add_u64 v[2:3], v[2:3], 0, v[184:185]
	v_lshl_add_u64 v[4:5], v[4:5], 0, v[184:185]
	v_lshl_add_u64 v[6:7], v[6:7], 0, v[184:185]
	s_lshl_b32 s24, s14, 1
	s_cmp_lt_u32 s66, 64
	s_cselect_b64 s[2:3], -1, 0
	v_lshl_add_u64 v[126:127], v[170:171], 0, s[24:25]
	v_lshl_add_u64 v[184:185], s[84:85], 0, v[184:185]
	s_and_b64 s[50:51], s[2:3], s[12:13]
	s_mov_b32 s24, s28
	s_waitcnt vmcnt(0)
	global_load_dwordx4 v[112:115], v[0:1], off
	global_load_dwordx4 v[116:119], v[2:3], off
	global_load_dwordx4 v[104:107], v[4:5], off
	global_load_dwordx4 v[108:111], v[6:7], off
	v_add_u32_e32 v0, s15, v205
	v_ashrrev_i32_e32 v1, 31, v0
	v_lshl_add_u64 v[122:123], s[42:43], 0, v[0:1]
	v_lshl_add_u64 v[124:125], s[44:45], 0, v[0:1]
	v_mov_b32_e32 v186, v48
	v_mov_b32_e32 v187, v50
	v_mov_b32_e32 v188, v49
	v_mov_b32_e32 v189, v51
	v_xor_b32_e32 v241, 0x80000000, v173
	v_xor_b32_e32 v242, 0x80000000, v175
	v_mov_b32_e32 v240, 0xbdd2d3e7
	s_waitcnt vmcnt(0)
	s_branch .LBB0_188

.LBB0_188:
	s_waitcnt vmcnt(9)
	v_mfma_f32_32x32x16_bf16 v[0:15], v[108:111], v[128:131], 0
	v_mfma_f32_32x32x16_bf16 v[16:31], v[108:111], v[132:135], 0
	v_mfma_f32_32x32x16_bf16 v[48:63], v[108:111], v[136:139], 0
	v_mfma_f32_32x32x16_bf16 v[32:47], v[108:111], v[140:143], 0
	v_add_u32_e32 v148, v200, v150
	ds_write_b128 v148, v[108:111] offset:8192
	s_cmp_gt_i32 s24, 0
	s_cselect_b64 s[2:3], -1, 0
	s_or_b64 s[14:15], s[2:3], s[50:51]
	s_nop 7
	v_fmac_f32_e32 v0, v172, v186
	v_fmac_f32_e32 v16, v174, v188
	v_fmac_f32_e32 v48, v172, v187
	v_fmac_f32_e32 v32, v174, v189
	v_fmac_f32_e32 v0, v241, v187
	v_fmac_f32_e32 v16, v242, v189
	v_fmac_f32_e32 v48, v173, v186
	v_fmac_f32_e32 v32, v175, v188
	v_fmac_f32_e32 v1, v172, v0
	v_fmac_f32_e32 v17, v174, v16
	v_fmac_f32_e32 v49, v172, v48
	v_fmac_f32_e32 v33, v174, v32
	v_fmac_f32_e32 v1, v241, v48
	v_fmac_f32_e32 v17, v242, v32
	v_fmac_f32_e32 v49, v173, v0
	v_fmac_f32_e32 v33, v175, v16
	v_fmac_f32_e32 v2, v172, v1
	v_fmac_f32_e32 v18, v174, v17
	v_fmac_f32_e32 v50, v172, v49
	v_fmac_f32_e32 v34, v174, v33
	v_fmac_f32_e32 v2, v241, v49
	v_fmac_f32_e32 v18, v242, v33
	v_fmac_f32_e32 v50, v173, v1
	v_fmac_f32_e32 v34, v175, v17
	v_fmac_f32_e32 v3, v172, v2
	v_fmac_f32_e32 v19, v174, v18
	v_fmac_f32_e32 v51, v172, v50
	v_fmac_f32_e32 v35, v174, v34
	v_fmac_f32_e32 v3, v241, v50
	v_fmac_f32_e32 v19, v242, v34
	v_fmac_f32_e32 v51, v173, v2
	v_fmac_f32_e32 v35, v175, v18
	v_cvt_pk_bf16_f32 v190, v0, v1
	v_cvt_pk_bf16_f32 v191, v2, v3
	v_cvt_pk_bf16_f32 v192, v16, v17
	v_cvt_pk_bf16_f32 v193, v18, v19
	ds_write2st64_b64 v207, v[190:191], v[192:193] offset1:4
	v_cvt_pk_bf16_f32 v212, v48, v49
	v_cvt_pk_bf16_f32 v213, v50, v51
	v_cvt_pk_bf16_f32 v214, v32, v33
	v_cvt_pk_bf16_f32 v215, v34, v35
	ds_write2st64_b64 v207, v[212:213], v[214:215] offset0:8 offset1:12
	v_fmac_f32_e32 v4, v172, v3
	v_fmac_f32_e32 v20, v174, v19
	v_fmac_f32_e32 v52, v172, v51
	v_fmac_f32_e32 v36, v174, v35
	v_fmac_f32_e32 v4, v241, v51
	v_fmac_f32_e32 v20, v242, v35
	v_fmac_f32_e32 v52, v173, v3
	v_fmac_f32_e32 v36, v175, v19
	v_fmac_f32_e32 v5, v172, v4
	v_fmac_f32_e32 v21, v174, v20
	v_fmac_f32_e32 v53, v172, v52
	v_fmac_f32_e32 v37, v174, v36
	v_fmac_f32_e32 v5, v241, v52
	v_fmac_f32_e32 v21, v242, v36
	v_fmac_f32_e32 v53, v173, v4
	v_fmac_f32_e32 v37, v175, v20
	v_fmac_f32_e32 v6, v172, v5
	v_fmac_f32_e32 v22, v174, v21
	v_fmac_f32_e32 v54, v172, v53
	v_fmac_f32_e32 v38, v174, v37
	v_fmac_f32_e32 v6, v241, v53
	v_fmac_f32_e32 v22, v242, v37
	v_fmac_f32_e32 v54, v173, v5
	v_fmac_f32_e32 v38, v175, v21
	v_fmac_f32_e32 v7, v172, v6
	v_fmac_f32_e32 v23, v174, v22
	v_fmac_f32_e32 v55, v172, v54
	v_fmac_f32_e32 v39, v174, v38
	v_fmac_f32_e32 v7, v241, v54
	v_fmac_f32_e32 v23, v242, v38
	v_fmac_f32_e32 v55, v173, v6
	v_fmac_f32_e32 v39, v175, v22
	v_cvt_pk_bf16_f32 v190, v4, v5
	v_cvt_pk_bf16_f32 v191, v6, v7
	v_cvt_pk_bf16_f32 v192, v20, v21
	v_cvt_pk_bf16_f32 v193, v22, v23
	ds_write2st64_b64 v208, v[190:191], v[192:193] offset1:4
	v_cvt_pk_bf16_f32 v212, v52, v53
	v_cvt_pk_bf16_f32 v213, v54, v55
	v_cvt_pk_bf16_f32 v214, v36, v37
	v_cvt_pk_bf16_f32 v215, v38, v39
	ds_write2st64_b64 v208, v[212:213], v[214:215] offset0:8 offset1:12
	v_fmac_f32_e32 v8, v172, v7
	v_fmac_f32_e32 v24, v174, v23
	v_fmac_f32_e32 v56, v172, v55
	v_fmac_f32_e32 v40, v174, v39
	v_fmac_f32_e32 v8, v241, v55
	v_fmac_f32_e32 v24, v242, v39
	v_fmac_f32_e32 v56, v173, v7
	v_fmac_f32_e32 v40, v175, v23
	v_fmac_f32_e32 v9, v172, v8
	v_fmac_f32_e32 v25, v174, v24
	v_fmac_f32_e32 v57, v172, v56
	v_fmac_f32_e32 v41, v174, v40
	v_fmac_f32_e32 v9, v241, v56
	v_fmac_f32_e32 v25, v242, v40
	v_fmac_f32_e32 v57, v173, v8
	v_fmac_f32_e32 v41, v175, v24
	v_fmac_f32_e32 v10, v172, v9
	v_fmac_f32_e32 v26, v174, v25
	v_fmac_f32_e32 v58, v172, v57
	v_fmac_f32_e32 v42, v174, v41
	v_fmac_f32_e32 v10, v241, v57
	v_fmac_f32_e32 v26, v242, v41
	v_fmac_f32_e32 v58, v173, v9
	v_fmac_f32_e32 v42, v175, v25
	v_fmac_f32_e32 v11, v172, v10
	v_fmac_f32_e32 v27, v174, v26
	v_fmac_f32_e32 v59, v172, v58
	v_fmac_f32_e32 v43, v174, v42
	v_fmac_f32_e32 v11, v241, v58
	v_fmac_f32_e32 v27, v242, v42
	v_fmac_f32_e32 v59, v173, v10
	v_fmac_f32_e32 v43, v175, v26
	v_cvt_pk_bf16_f32 v190, v8, v9
	v_cvt_pk_bf16_f32 v191, v10, v11
	v_cvt_pk_bf16_f32 v192, v24, v25
	v_cvt_pk_bf16_f32 v193, v26, v27
	ds_write2st64_b64 v209, v[190:191], v[192:193] offset1:4
	v_cvt_pk_bf16_f32 v212, v56, v57
	v_cvt_pk_bf16_f32 v213, v58, v59
	v_cvt_pk_bf16_f32 v214, v40, v41
	v_cvt_pk_bf16_f32 v215, v42, v43
	ds_write2st64_b64 v209, v[212:213], v[214:215] offset0:8 offset1:12
	v_fmac_f32_e32 v12, v172, v11
	v_fmac_f32_e32 v28, v174, v27
	v_fmac_f32_e32 v60, v172, v59
	v_fmac_f32_e32 v44, v174, v43
	v_fmac_f32_e32 v12, v241, v59
	v_fmac_f32_e32 v28, v242, v43
	v_fmac_f32_e32 v60, v173, v11
	v_fmac_f32_e32 v44, v175, v27
	v_fmac_f32_e32 v13, v172, v12
	v_fmac_f32_e32 v29, v174, v28
	v_fmac_f32_e32 v61, v172, v60
	v_fmac_f32_e32 v45, v174, v44
	v_fmac_f32_e32 v13, v241, v60
	v_fmac_f32_e32 v29, v242, v44
	v_fmac_f32_e32 v61, v173, v12
	v_fmac_f32_e32 v45, v175, v28
	v_fmac_f32_e32 v14, v172, v13
	v_fmac_f32_e32 v30, v174, v29
	v_fmac_f32_e32 v62, v172, v61
	v_fmac_f32_e32 v46, v174, v45
	v_fmac_f32_e32 v14, v241, v61
	v_fmac_f32_e32 v30, v242, v45
	v_fmac_f32_e32 v62, v173, v13
	v_fmac_f32_e32 v46, v175, v29
	v_fmac_f32_e32 v15, v172, v14
	v_fmac_f32_e32 v31, v174, v30
	v_fmac_f32_e32 v63, v172, v62
	v_fmac_f32_e32 v47, v174, v46
	v_fmac_f32_e32 v15, v241, v62
	v_fmac_f32_e32 v31, v242, v46
	v_fmac_f32_e32 v63, v173, v14
	v_fmac_f32_e32 v47, v175, v30
	v_mov_b32_e32 v186, v15
	v_mov_b32_e32 v187, v63
	v_mov_b32_e32 v188, v31
	v_mov_b32_e32 v189, v47
	v_cvt_pk_bf16_f32 v190, v12, v13
	v_cvt_pk_bf16_f32 v191, v14, v15
	v_cvt_pk_bf16_f32 v192, v28, v29
	v_cvt_pk_bf16_f32 v193, v30, v31
	ds_write2st64_b64 v210, v[190:191], v[192:193] offset1:4
	v_cvt_pk_bf16_f32 v212, v60, v61
	v_cvt_pk_bf16_f32 v213, v62, v63
	v_cvt_pk_bf16_f32 v214, v44, v45
	v_cvt_pk_bf16_f32 v215, v46, v47
	ds_write2st64_b64 v210, v[212:213], v[214:215] offset0:8 offset1:12
	s_waitcnt lgkmcnt(0)
	ds_read_b64_tr_b16 v[0:1], v151 offset:0
	ds_read_b64_tr_b16 v[2:3], v199 offset:0
	ds_read_b64_tr_b16 v[28:29], v151 offset:1024
	ds_read_b64_tr_b16 v[30:31], v199 offset:1024
	ds_read_b64_tr_b16 v[24:25], v151 offset:2048
	ds_read_b64_tr_b16 v[26:27], v199 offset:2048
	ds_read_b64_tr_b16 v[20:21], v151 offset:3072
	ds_read_b64_tr_b16 v[22:23], v199 offset:3072
	ds_read_b64_tr_b16 v[16:17], v151 offset:4096
	ds_read_b64_tr_b16 v[18:19], v199 offset:4096
	ds_read_b64_tr_b16 v[44:45], v151 offset:5120
	ds_read_b64_tr_b16 v[46:47], v199 offset:5120
	ds_read_b64_tr_b16 v[40:41], v151 offset:6144
	ds_read_b64_tr_b16 v[42:43], v199 offset:6144
	ds_read_b64_tr_b16 v[52:53], v151 offset:7168
	ds_read_b64_tr_b16 v[54:55], v199 offset:7168
	s_waitcnt lgkmcnt(0)
	s_nop 0
	v_mfma_f32_32x32x16_bf16 v[0:15], v[68:71], v[0:3], 0
	v_mfma_f32_32x32x16_bf16 v[0:15], v[64:67], v[28:31], v[0:15]
	v_mfma_f32_32x32x16_bf16 v[0:15], v[76:79], v[24:27], v[0:15]
	v_mfma_f32_32x32x16_bf16 v[0:15], v[72:75], v[20:23], v[0:15]
	v_mfma_f32_32x32x16_bf16 v[0:15], v[84:87], v[16:19], v[0:15]
	v_mfma_f32_32x32x16_bf16 v[0:15], v[80:83], v[44:47], v[0:15]
	v_mfma_f32_32x32x16_bf16 v[0:15], v[92:95], v[40:43], v[0:15]
	v_mfma_f32_32x32x16_bf16 v[0:15], v[88:91], v[52:55], v[0:15]
	s_and_saveexec_b64 s[2:3], s[14:15]
	s_cbranch_execz .LBB0_190
	s_nop 7
	v_add_u32_e32 v16, v200, v146
	v_add_u32_e32 v16, 0x2000, v16
	ds_read2_b64 v[16:19], v16 offset1:2
	s_waitcnt lgkmcnt(0)
	v_lshlrev_b32_e32 v10, 16, v19
	v_and_b32_e32 v11, 0xffff0000, v19
	v_pk_fma_f32 v[6:7], v[102:103], v[10:11], v[6:7]
	s_nop 0
	v_mul_f32_e32 v10, v7, v7
	v_fmaak_f32 v10, v240, v10, 0xc0135761
	v_mul_f32_e32 v11, v6, v6
	v_mul_f32_e32 v10, v7, v10
	v_fmaak_f32 v11, v240, v11, 0xc0135761
	v_mul_f32_e32 v11, v6, v11
	v_exp_f32_e32 v10, v10
	v_exp_f32_e32 v11, v11
	v_add_f32_e32 v8, 1.0, v10
	v_rcp_f32_e32 v9, v8
	v_add_f32_e32 v8, 1.0, v11
	v_lshlrev_b32_e32 v10, 16, v18
	v_and_b32_e32 v11, 0xffff0000, v18
	v_pk_fma_f32 v[4:5], v[100:101], v[10:11], v[4:5]
	v_and_b32_e32 v13, 0xffff0000, v17
	v_mul_f32_e32 v10, v5, v5
	v_fmaak_f32 v10, v240, v10, 0xc0135761
	v_mul_f32_e32 v11, v4, v4
	v_mul_f32_e32 v10, v5, v10
	v_fmaak_f32 v11, v240, v11, 0xc0135761
	v_mul_f32_e32 v11, v4, v11
	v_exp_f32_e32 v10, v10
	v_exp_f32_e32 v12, v11
	v_and_b32_e32 v15, 0xffff0000, v16
	v_add_f32_e32 v10, 1.0, v10
	v_rcp_f32_e32 v11, v10
	v_add_f32_e32 v10, 1.0, v12
	v_lshlrev_b32_e32 v12, 16, v17
	v_pk_fma_f32 v[2:3], v[98:99], v[12:13], v[2:3]
	v_rcp_f32_e32 v8, v8
	v_mul_f32_e32 v12, v3, v3
	v_fmaak_f32 v12, v240, v12, 0xc0135761
	v_mul_f32_e32 v13, v2, v2
	v_mul_f32_e32 v12, v3, v12
	v_fmaak_f32 v13, v240, v13, 0xc0135761
	v_mul_f32_e32 v13, v2, v13
	v_exp_f32_e32 v12, v12
	v_exp_f32_e32 v14, v13
	v_rcp_f32_e32 v10, v10
	v_add_f32_e32 v12, 1.0, v12
	v_rcp_f32_e32 v13, v12
	v_add_f32_e32 v12, 1.0, v14
	v_lshlrev_b32_e32 v14, 16, v16
	v_pk_fma_f32 v[0:1], v[96:97], v[14:15], v[0:1]
	v_rcp_f32_e32 v12, v12
	v_mul_f32_e32 v14, v1, v1
	v_fmaak_f32 v14, v240, v14, 0xc0135761
	v_mul_f32_e32 v15, v0, v0
	v_mul_f32_e32 v14, v1, v14
	v_fmaak_f32 v15, v240, v15, 0xc0135761
	v_mul_f32_e32 v15, v0, v15
	v_exp_f32_e32 v14, v14
	v_exp_f32_e32 v16, v15
	s_cmp_eq_u32 s24, 0
	v_add_f32_e32 v14, 1.0, v14
	v_rcp_f32_e32 v15, v14
	v_add_f32_e32 v14, 1.0, v16
	v_rcp_f32_e32 v14, v14
	s_cselect_b64 vcc, -1, 0
	v_pk_mul_f32 v[6:7], v[6:7], v[8:9]
	v_cndmask_b32_e64 v9, v123, 0, vcc
	v_cndmask_b32_e32 v8, v122, v154, vcc
	v_pk_mul_f32 v[2:3], v[2:3], v[12:13]
	v_pk_mul_f32 v[0:1], v[0:1], v[14:15]
	v_lshlrev_b64 v[8:9], 11, v[8:9]
	v_pk_mul_f32 v[4:5], v[4:5], v[10:11]
	v_lshl_add_u64 v[8:9], v[126:127], 0, v[8:9]
	v_cvt_pk_bf16_f32 v0, v0, v1
	v_cvt_pk_bf16_f32 v1, v2, v3
	v_cvt_pk_bf16_f32 v2, v4, v5
	v_cvt_pk_bf16_f32 v3, v6, v7
	global_store_dwordx2 v[8:9], v[0:1], off
	global_store_dwordx2 v[8:9], v[2:3], off offset:16
.LBB0_190:
	s_or_b64 exec, exec, s[2:3]
	s_add_i32 s67, s24, 4
	s_min_i32 s2, s67, s23
	s_nop 0
	v_sub_co_u32_e64 v0, vcc, s2, 1
	v_ashrrev_i32_e32 v1, 31, v0
	v_lshl_add_u64 v[0:1], v[0:1], 4, v[120:121]
	v_cndmask_b32_e64 v1, v1, 0, vcc
	v_cndmask_b32_e32 v0, v0, v154, vcc
	v_lshlrev_b64 v[0:1], 11, v[0:1]
	v_lshl_add_u64 v[0:1], v[184:185], 0, v[0:1]
	global_load_dwordx4 v[108:111], v[0:1], off
	s_add_i32 s52, s24, 1
	s_cmp_ge_i32 s52, s22
	s_cbranch_scc1 .LBB0_195
	s_waitcnt vmcnt(9)
	v_mfma_f32_32x32x16_bf16 v[0:15], v[104:107], v[128:131], 0
	v_mfma_f32_32x32x16_bf16 v[16:31], v[104:107], v[132:135], 0
	v_mfma_f32_32x32x16_bf16 v[48:63], v[104:107], v[136:139], 0
	v_mfma_f32_32x32x16_bf16 v[32:47], v[104:107], v[140:143], 0
	ds_write_b128 v148, v[104:107] offset:8192
	s_cmp_gt_i32 s24, -1
	s_cselect_b64 s[2:3], -1, 0
	s_or_b64 s[14:15], s[2:3], s[50:51]
	s_nop 7
	v_fmac_f32_e32 v0, v172, v186
	v_fmac_f32_e32 v16, v174, v188
	v_fmac_f32_e32 v48, v172, v187
	v_fmac_f32_e32 v32, v174, v189
	v_fmac_f32_e32 v0, v241, v187
	v_fmac_f32_e32 v16, v242, v189
	v_fmac_f32_e32 v48, v173, v186
	v_fmac_f32_e32 v32, v175, v188
	v_fmac_f32_e32 v1, v172, v0
	v_fmac_f32_e32 v17, v174, v16
	v_fmac_f32_e32 v49, v172, v48
	v_fmac_f32_e32 v33, v174, v32
	v_fmac_f32_e32 v1, v241, v48
	v_fmac_f32_e32 v17, v242, v32
	v_fmac_f32_e32 v49, v173, v0
	v_fmac_f32_e32 v33, v175, v16
	v_fmac_f32_e32 v2, v172, v1
	v_fmac_f32_e32 v18, v174, v17
	v_fmac_f32_e32 v50, v172, v49
	v_fmac_f32_e32 v34, v174, v33
	v_fmac_f32_e32 v2, v241, v49
	v_fmac_f32_e32 v18, v242, v33
	v_fmac_f32_e32 v50, v173, v1
	v_fmac_f32_e32 v34, v175, v17
	v_fmac_f32_e32 v3, v172, v2
	v_fmac_f32_e32 v19, v174, v18
	v_fmac_f32_e32 v51, v172, v50
	v_fmac_f32_e32 v35, v174, v34
	v_fmac_f32_e32 v3, v241, v50
	v_fmac_f32_e32 v19, v242, v34
	v_fmac_f32_e32 v51, v173, v2
	v_fmac_f32_e32 v35, v175, v18
	v_cvt_pk_bf16_f32 v190, v0, v1
	v_cvt_pk_bf16_f32 v191, v2, v3
	v_cvt_pk_bf16_f32 v192, v16, v17
	v_cvt_pk_bf16_f32 v193, v18, v19
	ds_write2st64_b64 v207, v[190:191], v[192:193] offset1:4
	v_cvt_pk_bf16_f32 v212, v48, v49
	v_cvt_pk_bf16_f32 v213, v50, v51
	v_cvt_pk_bf16_f32 v214, v32, v33
	v_cvt_pk_bf16_f32 v215, v34, v35
	ds_write2st64_b64 v207, v[212:213], v[214:215] offset0:8 offset1:12
	v_fmac_f32_e32 v4, v172, v3
	v_fmac_f32_e32 v20, v174, v19
	v_fmac_f32_e32 v52, v172, v51
	v_fmac_f32_e32 v36, v174, v35
	v_fmac_f32_e32 v4, v241, v51
	v_fmac_f32_e32 v20, v242, v35
	v_fmac_f32_e32 v52, v173, v3
	v_fmac_f32_e32 v36, v175, v19
	v_fmac_f32_e32 v5, v172, v4
	v_fmac_f32_e32 v21, v174, v20
	v_fmac_f32_e32 v53, v172, v52
	v_fmac_f32_e32 v37, v174, v36
	v_fmac_f32_e32 v5, v241, v52
	v_fmac_f32_e32 v21, v242, v36
	v_fmac_f32_e32 v53, v173, v4
	v_fmac_f32_e32 v37, v175, v20
	v_fmac_f32_e32 v6, v172, v5
	v_fmac_f32_e32 v22, v174, v21
	v_fmac_f32_e32 v54, v172, v53
	v_fmac_f32_e32 v38, v174, v37
	v_fmac_f32_e32 v6, v241, v53
	v_fmac_f32_e32 v22, v242, v37
	v_fmac_f32_e32 v54, v173, v5
	v_fmac_f32_e32 v38, v175, v21
	v_fmac_f32_e32 v7, v172, v6
	v_fmac_f32_e32 v23, v174, v22
	v_fmac_f32_e32 v55, v172, v54
	v_fmac_f32_e32 v39, v174, v38
	v_fmac_f32_e32 v7, v241, v54
	v_fmac_f32_e32 v23, v242, v38
	v_fmac_f32_e32 v55, v173, v6
	v_fmac_f32_e32 v39, v175, v22
	v_cvt_pk_bf16_f32 v190, v4, v5
	v_cvt_pk_bf16_f32 v191, v6, v7
	v_cvt_pk_bf16_f32 v192, v20, v21
	v_cvt_pk_bf16_f32 v193, v22, v23
	ds_write2st64_b64 v208, v[190:191], v[192:193] offset1:4
	v_cvt_pk_bf16_f32 v212, v52, v53
	v_cvt_pk_bf16_f32 v213, v54, v55
	v_cvt_pk_bf16_f32 v214, v36, v37
	v_cvt_pk_bf16_f32 v215, v38, v39
	ds_write2st64_b64 v208, v[212:213], v[214:215] offset0:8 offset1:12
	v_fmac_f32_e32 v8, v172, v7
	v_fmac_f32_e32 v24, v174, v23
	v_fmac_f32_e32 v56, v172, v55
	v_fmac_f32_e32 v40, v174, v39
	v_fmac_f32_e32 v8, v241, v55
	v_fmac_f32_e32 v24, v242, v39
	v_fmac_f32_e32 v56, v173, v7
	v_fmac_f32_e32 v40, v175, v23
	v_fmac_f32_e32 v9, v172, v8
	v_fmac_f32_e32 v25, v174, v24
	v_fmac_f32_e32 v57, v172, v56
	v_fmac_f32_e32 v41, v174, v40
	v_fmac_f32_e32 v9, v241, v56
	v_fmac_f32_e32 v25, v242, v40
	v_fmac_f32_e32 v57, v173, v8
	v_fmac_f32_e32 v41, v175, v24
	v_fmac_f32_e32 v10, v172, v9
	v_fmac_f32_e32 v26, v174, v25
	v_fmac_f32_e32 v58, v172, v57
	v_fmac_f32_e32 v42, v174, v41
	v_fmac_f32_e32 v10, v241, v57
	v_fmac_f32_e32 v26, v242, v41
	v_fmac_f32_e32 v58, v173, v9
	v_fmac_f32_e32 v42, v175, v25
	v_fmac_f32_e32 v11, v172, v10
	v_fmac_f32_e32 v27, v174, v26
	v_fmac_f32_e32 v59, v172, v58
	v_fmac_f32_e32 v43, v174, v42
	v_fmac_f32_e32 v11, v241, v58
	v_fmac_f32_e32 v27, v242, v42
	v_fmac_f32_e32 v59, v173, v10
	v_fmac_f32_e32 v43, v175, v26
	v_cvt_pk_bf16_f32 v190, v8, v9
	v_cvt_pk_bf16_f32 v191, v10, v11
	v_cvt_pk_bf16_f32 v192, v24, v25
	v_cvt_pk_bf16_f32 v193, v26, v27
	ds_write2st64_b64 v209, v[190:191], v[192:193] offset1:4
	v_cvt_pk_bf16_f32 v212, v56, v57
	v_cvt_pk_bf16_f32 v213, v58, v59
	v_cvt_pk_bf16_f32 v214, v40, v41
	v_cvt_pk_bf16_f32 v215, v42, v43
	ds_write2st64_b64 v209, v[212:213], v[214:215] offset0:8 offset1:12
	v_fmac_f32_e32 v12, v172, v11
	v_fmac_f32_e32 v28, v174, v27
	v_fmac_f32_e32 v60, v172, v59
	v_fmac_f32_e32 v44, v174, v43
	v_fmac_f32_e32 v12, v241, v59
	v_fmac_f32_e32 v28, v242, v43
	v_fmac_f32_e32 v60, v173, v11
	v_fmac_f32_e32 v44, v175, v27
	v_fmac_f32_e32 v13, v172, v12
	v_fmac_f32_e32 v29, v174, v28
	v_fmac_f32_e32 v61, v172, v60
	v_fmac_f32_e32 v45, v174, v44
	v_fmac_f32_e32 v13, v241, v60
	v_fmac_f32_e32 v29, v242, v44
	v_fmac_f32_e32 v61, v173, v12
	v_fmac_f32_e32 v45, v175, v28
	v_fmac_f32_e32 v14, v172, v13
	v_fmac_f32_e32 v30, v174, v29
	v_fmac_f32_e32 v62, v172, v61
	v_fmac_f32_e32 v46, v174, v45
	v_fmac_f32_e32 v14, v241, v61
	v_fmac_f32_e32 v30, v242, v45
	v_fmac_f32_e32 v62, v173, v13
	v_fmac_f32_e32 v46, v175, v29
	v_fmac_f32_e32 v15, v172, v14
	v_fmac_f32_e32 v31, v174, v30
	v_fmac_f32_e32 v63, v172, v62
	v_fmac_f32_e32 v47, v174, v46
	v_fmac_f32_e32 v15, v241, v62
	v_fmac_f32_e32 v31, v242, v46
	v_fmac_f32_e32 v63, v173, v14
	v_fmac_f32_e32 v47, v175, v30
	v_mov_b32_e32 v186, v15
	v_mov_b32_e32 v187, v63
	v_mov_b32_e32 v188, v31
	v_mov_b32_e32 v189, v47
	v_cvt_pk_bf16_f32 v190, v12, v13
	v_cvt_pk_bf16_f32 v191, v14, v15
	v_cvt_pk_bf16_f32 v192, v28, v29
	v_cvt_pk_bf16_f32 v193, v30, v31
	ds_write2st64_b64 v210, v[190:191], v[192:193] offset1:4
	v_cvt_pk_bf16_f32 v212, v60, v61
	v_cvt_pk_bf16_f32 v213, v62, v63
	v_cvt_pk_bf16_f32 v214, v44, v45
	v_cvt_pk_bf16_f32 v215, v46, v47
	ds_write2st64_b64 v210, v[212:213], v[214:215] offset0:8 offset1:12
	s_waitcnt lgkmcnt(0)
	ds_read_b64_tr_b16 v[0:1], v151 offset:0
	ds_read_b64_tr_b16 v[2:3], v199 offset:0
	ds_read_b64_tr_b16 v[28:29], v151 offset:1024
	ds_read_b64_tr_b16 v[30:31], v199 offset:1024
	ds_read_b64_tr_b16 v[24:25], v151 offset:2048
	ds_read_b64_tr_b16 v[26:27], v199 offset:2048
	ds_read_b64_tr_b16 v[20:21], v151 offset:3072
	ds_read_b64_tr_b16 v[22:23], v199 offset:3072
	ds_read_b64_tr_b16 v[16:17], v151 offset:4096
	ds_read_b64_tr_b16 v[18:19], v199 offset:4096
	ds_read_b64_tr_b16 v[44:45], v151 offset:5120
	ds_read_b64_tr_b16 v[46:47], v199 offset:5120
	ds_read_b64_tr_b16 v[40:41], v151 offset:6144
	ds_read_b64_tr_b16 v[42:43], v199 offset:6144
	ds_read_b64_tr_b16 v[52:53], v151 offset:7168
	ds_read_b64_tr_b16 v[54:55], v199 offset:7168
	s_waitcnt lgkmcnt(0)
	s_nop 0
	v_mfma_f32_32x32x16_bf16 v[0:15], v[68:71], v[0:3], 0
	v_mfma_f32_32x32x16_bf16 v[0:15], v[64:67], v[28:31], v[0:15]
	v_mfma_f32_32x32x16_bf16 v[0:15], v[76:79], v[24:27], v[0:15]
	v_mfma_f32_32x32x16_bf16 v[0:15], v[72:75], v[20:23], v[0:15]
	v_mfma_f32_32x32x16_bf16 v[0:15], v[84:87], v[16:19], v[0:15]
	v_mfma_f32_32x32x16_bf16 v[0:15], v[80:83], v[44:47], v[0:15]
	v_mfma_f32_32x32x16_bf16 v[0:15], v[92:95], v[40:43], v[0:15]
	v_mfma_f32_32x32x16_bf16 v[0:15], v[88:91], v[52:55], v[0:15]
	s_and_saveexec_b64 s[2:3], s[14:15]
	s_cbranch_execz .LBB0_193
	s_nop 7
	v_add_u32_e32 v16, v200, v146
	v_add_u32_e32 v16, 0x2000, v16
	ds_read2_b64 v[16:19], v16 offset1:2
	s_waitcnt lgkmcnt(0)
	v_lshlrev_b32_e32 v10, 16, v19
	v_and_b32_e32 v11, 0xffff0000, v19
	v_pk_fma_f32 v[6:7], v[102:103], v[10:11], v[6:7]
	s_nop 0
	v_mul_f32_e32 v10, v7, v7
	v_fmaak_f32 v10, v240, v10, 0xc0135761
	v_mul_f32_e32 v11, v6, v6
	v_mul_f32_e32 v10, v7, v10
	v_fmaak_f32 v11, v240, v11, 0xc0135761
	v_mul_f32_e32 v11, v6, v11
	v_exp_f32_e32 v10, v10
	v_exp_f32_e32 v11, v11
	v_add_f32_e32 v8, 1.0, v10
	v_rcp_f32_e32 v9, v8
	v_add_f32_e32 v8, 1.0, v11
	v_lshlrev_b32_e32 v10, 16, v18
	v_and_b32_e32 v11, 0xffff0000, v18
	v_pk_fma_f32 v[4:5], v[100:101], v[10:11], v[4:5]
	v_and_b32_e32 v13, 0xffff0000, v17
	v_mul_f32_e32 v10, v5, v5
	v_fmaak_f32 v10, v240, v10, 0xc0135761
	v_mul_f32_e32 v11, v4, v4
	v_mul_f32_e32 v10, v5, v10
	v_fmaak_f32 v11, v240, v11, 0xc0135761
	v_mul_f32_e32 v11, v4, v11
	v_exp_f32_e32 v10, v10
	v_exp_f32_e32 v12, v11
	v_and_b32_e32 v15, 0xffff0000, v16
	v_add_f32_e32 v10, 1.0, v10
	v_rcp_f32_e32 v11, v10
	v_add_f32_e32 v10, 1.0, v12
	v_lshlrev_b32_e32 v12, 16, v17
	v_pk_fma_f32 v[2:3], v[98:99], v[12:13], v[2:3]
	v_rcp_f32_e32 v8, v8
	v_mul_f32_e32 v12, v3, v3
	v_fmaak_f32 v12, v240, v12, 0xc0135761
	v_mul_f32_e32 v13, v2, v2
	v_mul_f32_e32 v12, v3, v12
	v_fmaak_f32 v13, v240, v13, 0xc0135761
	v_mul_f32_e32 v13, v2, v13
	v_exp_f32_e32 v12, v12
	v_exp_f32_e32 v14, v13
	v_rcp_f32_e32 v10, v10
	v_add_f32_e32 v12, 1.0, v12
	v_rcp_f32_e32 v13, v12
	v_add_f32_e32 v12, 1.0, v14
	v_lshlrev_b32_e32 v14, 16, v16
	v_pk_fma_f32 v[0:1], v[96:97], v[14:15], v[0:1]
	v_rcp_f32_e32 v12, v12
	v_mul_f32_e32 v14, v1, v1
	v_fmaak_f32 v14, v240, v14, 0xc0135761
	v_mul_f32_e32 v15, v0, v0
	v_mul_f32_e32 v14, v1, v14
	v_fmaak_f32 v15, v240, v15, 0xc0135761
	v_mul_f32_e32 v15, v0, v15
	v_exp_f32_e32 v14, v14
	v_exp_f32_e32 v16, v15
	s_cmp_eq_u32 s24, -1
	v_add_f32_e32 v14, 1.0, v14
	v_rcp_f32_e32 v15, v14
	v_add_f32_e32 v14, 1.0, v16
	v_rcp_f32_e32 v14, v14
	s_cselect_b64 vcc, -1, 0
	v_pk_mul_f32 v[6:7], v[6:7], v[8:9]
	v_cndmask_b32_e64 v9, v125, 0, vcc
	v_cndmask_b32_e32 v8, v124, v154, vcc
	v_pk_mul_f32 v[2:3], v[2:3], v[12:13]
	v_pk_mul_f32 v[0:1], v[0:1], v[14:15]
	v_lshlrev_b64 v[8:9], 11, v[8:9]
	v_pk_mul_f32 v[4:5], v[4:5], v[10:11]
	v_lshl_add_u64 v[8:9], v[126:127], 0, v[8:9]
	v_cvt_pk_bf16_f32 v0, v0, v1
	v_cvt_pk_bf16_f32 v1, v2, v3
	v_cvt_pk_bf16_f32 v2, v4, v5
	v_cvt_pk_bf16_f32 v3, v6, v7
	global_store_dwordx2 v[8:9], v[0:1], off
	global_store_dwordx2 v[8:9], v[2:3], off offset:16

.LBB0_196:
	s_waitcnt vmcnt(9)
	v_mfma_f32_32x32x16_bf16 v[0:15], v[116:119], v[128:131], 0
	v_mfma_f32_32x32x16_bf16 v[16:31], v[116:119], v[132:135], 0
	v_mfma_f32_32x32x16_bf16 v[48:63], v[116:119], v[136:139], 0
	v_mfma_f32_32x32x16_bf16 v[32:47], v[116:119], v[140:143], 0
	ds_write_b128 v148, v[116:119] offset:8192
	s_cmp_gt_i32 s24, -2
	s_cselect_b64 s[2:3], -1, 0
	s_or_b64 s[68:69], s[2:3], s[50:51]
	s_nop 7
	v_fmac_f32_e32 v0, v172, v186
	v_fmac_f32_e32 v16, v174, v188
	v_fmac_f32_e32 v48, v172, v187
	v_fmac_f32_e32 v32, v174, v189
	v_fmac_f32_e32 v0, v241, v187
	v_fmac_f32_e32 v16, v242, v189
	v_fmac_f32_e32 v48, v173, v186
	v_fmac_f32_e32 v32, v175, v188
	v_fmac_f32_e32 v1, v172, v0
	v_fmac_f32_e32 v17, v174, v16
	v_fmac_f32_e32 v49, v172, v48
	v_fmac_f32_e32 v33, v174, v32
	v_fmac_f32_e32 v1, v241, v48
	v_fmac_f32_e32 v17, v242, v32
	v_fmac_f32_e32 v49, v173, v0
	v_fmac_f32_e32 v33, v175, v16
	v_fmac_f32_e32 v2, v172, v1
	v_fmac_f32_e32 v18, v174, v17
	v_fmac_f32_e32 v50, v172, v49
	v_fmac_f32_e32 v34, v174, v33
	v_fmac_f32_e32 v2, v241, v49
	v_fmac_f32_e32 v18, v242, v33
	v_fmac_f32_e32 v50, v173, v1
	v_fmac_f32_e32 v34, v175, v17
	v_fmac_f32_e32 v3, v172, v2
	v_fmac_f32_e32 v19, v174, v18
	v_fmac_f32_e32 v51, v172, v50
	v_fmac_f32_e32 v35, v174, v34
	v_fmac_f32_e32 v3, v241, v50
	v_fmac_f32_e32 v19, v242, v34
	v_fmac_f32_e32 v51, v173, v2
	v_fmac_f32_e32 v35, v175, v18
	v_cvt_pk_bf16_f32 v190, v0, v1
	v_cvt_pk_bf16_f32 v191, v2, v3
	v_cvt_pk_bf16_f32 v192, v16, v17
	v_cvt_pk_bf16_f32 v193, v18, v19
	ds_write2st64_b64 v207, v[190:191], v[192:193] offset1:4
	v_cvt_pk_bf16_f32 v212, v48, v49
	v_cvt_pk_bf16_f32 v213, v50, v51
	v_cvt_pk_bf16_f32 v214, v32, v33
	v_cvt_pk_bf16_f32 v215, v34, v35
	ds_write2st64_b64 v207, v[212:213], v[214:215] offset0:8 offset1:12
	v_fmac_f32_e32 v4, v172, v3
	v_fmac_f32_e32 v20, v174, v19
	v_fmac_f32_e32 v52, v172, v51
	v_fmac_f32_e32 v36, v174, v35
	v_fmac_f32_e32 v4, v241, v51
	v_fmac_f32_e32 v20, v242, v35
	v_fmac_f32_e32 v52, v173, v3
	v_fmac_f32_e32 v36, v175, v19
	v_fmac_f32_e32 v5, v172, v4
	v_fmac_f32_e32 v21, v174, v20
	v_fmac_f32_e32 v53, v172, v52
	v_fmac_f32_e32 v37, v174, v36
	v_fmac_f32_e32 v5, v241, v52
	v_fmac_f32_e32 v21, v242, v36
	v_fmac_f32_e32 v53, v173, v4
	v_fmac_f32_e32 v37, v175, v20
	v_fmac_f32_e32 v6, v172, v5
	v_fmac_f32_e32 v22, v174, v21
	v_fmac_f32_e32 v54, v172, v53
	v_fmac_f32_e32 v38, v174, v37
	v_fmac_f32_e32 v6, v241, v53
	v_fmac_f32_e32 v22, v242, v37
	v_fmac_f32_e32 v54, v173, v5
	v_fmac_f32_e32 v38, v175, v21
	v_fmac_f32_e32 v7, v172, v6
	v_fmac_f32_e32 v23, v174, v22
	v_fmac_f32_e32 v55, v172, v54
	v_fmac_f32_e32 v39, v174, v38
	v_fmac_f32_e32 v7, v241, v54
	v_fmac_f32_e32 v23, v242, v38
	v_fmac_f32_e32 v55, v173, v6
	v_fmac_f32_e32 v39, v175, v22
	v_cvt_pk_bf16_f32 v190, v4, v5
	v_cvt_pk_bf16_f32 v191, v6, v7
	v_cvt_pk_bf16_f32 v192, v20, v21
	v_cvt_pk_bf16_f32 v193, v22, v23
	ds_write2st64_b64 v208, v[190:191], v[192:193] offset1:4
	v_cvt_pk_bf16_f32 v212, v52, v53
	v_cvt_pk_bf16_f32 v213, v54, v55
	v_cvt_pk_bf16_f32 v214, v36, v37
	v_cvt_pk_bf16_f32 v215, v38, v39
	ds_write2st64_b64 v208, v[212:213], v[214:215] offset0:8 offset1:12
	v_fmac_f32_e32 v8, v172, v7
	v_fmac_f32_e32 v24, v174, v23
	v_fmac_f32_e32 v56, v172, v55
	v_fmac_f32_e32 v40, v174, v39
	v_fmac_f32_e32 v8, v241, v55
	v_fmac_f32_e32 v24, v242, v39
	v_fmac_f32_e32 v56, v173, v7
	v_fmac_f32_e32 v40, v175, v23
	v_fmac_f32_e32 v9, v172, v8
	v_fmac_f32_e32 v25, v174, v24
	v_fmac_f32_e32 v57, v172, v56
	v_fmac_f32_e32 v41, v174, v40
	v_fmac_f32_e32 v9, v241, v56
	v_fmac_f32_e32 v25, v242, v40
	v_fmac_f32_e32 v57, v173, v8
	v_fmac_f32_e32 v41, v175, v24
	v_fmac_f32_e32 v10, v172, v9
	v_fmac_f32_e32 v26, v174, v25
	v_fmac_f32_e32 v58, v172, v57
	v_fmac_f32_e32 v42, v174, v41
	v_fmac_f32_e32 v10, v241, v57
	v_fmac_f32_e32 v26, v242, v41
	v_fmac_f32_e32 v58, v173, v9
	v_fmac_f32_e32 v42, v175, v25
	v_fmac_f32_e32 v11, v172, v10
	v_fmac_f32_e32 v27, v174, v26
	v_fmac_f32_e32 v59, v172, v58
	v_fmac_f32_e32 v43, v174, v42
	v_fmac_f32_e32 v11, v241, v58
	v_fmac_f32_e32 v27, v242, v42
	v_fmac_f32_e32 v59, v173, v10
	v_fmac_f32_e32 v43, v175, v26
	v_cvt_pk_bf16_f32 v190, v8, v9
	v_cvt_pk_bf16_f32 v191, v10, v11
	v_cvt_pk_bf16_f32 v192, v24, v25
	v_cvt_pk_bf16_f32 v193, v26, v27
	ds_write2st64_b64 v209, v[190:191], v[192:193] offset1:4
	v_cvt_pk_bf16_f32 v212, v56, v57
	v_cvt_pk_bf16_f32 v213, v58, v59
	v_cvt_pk_bf16_f32 v214, v40, v41
	v_cvt_pk_bf16_f32 v215, v42, v43
	ds_write2st64_b64 v209, v[212:213], v[214:215] offset0:8 offset1:12
	v_fmac_f32_e32 v12, v172, v11
	v_fmac_f32_e32 v28, v174, v27
	v_fmac_f32_e32 v60, v172, v59
	v_fmac_f32_e32 v44, v174, v43
	v_fmac_f32_e32 v12, v241, v59
	v_fmac_f32_e32 v28, v242, v43
	v_fmac_f32_e32 v60, v173, v11
	v_fmac_f32_e32 v44, v175, v27
	v_fmac_f32_e32 v13, v172, v12
	v_fmac_f32_e32 v29, v174, v28
	v_fmac_f32_e32 v61, v172, v60
	v_fmac_f32_e32 v45, v174, v44
	v_fmac_f32_e32 v13, v241, v60
	v_fmac_f32_e32 v29, v242, v44
	v_fmac_f32_e32 v61, v173, v12
	v_fmac_f32_e32 v45, v175, v28
	v_fmac_f32_e32 v14, v172, v13
	v_fmac_f32_e32 v30, v174, v29
	v_fmac_f32_e32 v62, v172, v61
	v_fmac_f32_e32 v46, v174, v45
	v_fmac_f32_e32 v14, v241, v61
	v_fmac_f32_e32 v30, v242, v45
	v_fmac_f32_e32 v62, v173, v13
	v_fmac_f32_e32 v46, v175, v29
	v_fmac_f32_e32 v15, v172, v14
	v_fmac_f32_e32 v31, v174, v30
	v_fmac_f32_e32 v63, v172, v62
	v_fmac_f32_e32 v47, v174, v46
	v_fmac_f32_e32 v15, v241, v62
	v_fmac_f32_e32 v31, v242, v46
	v_fmac_f32_e32 v63, v173, v14
	v_fmac_f32_e32 v47, v175, v30
	v_mov_b32_e32 v186, v15
	v_mov_b32_e32 v187, v63
	v_mov_b32_e32 v188, v31
	v_mov_b32_e32 v189, v47
	v_cvt_pk_bf16_f32 v190, v12, v13
	v_cvt_pk_bf16_f32 v191, v14, v15
	v_cvt_pk_bf16_f32 v192, v28, v29
	v_cvt_pk_bf16_f32 v193, v30, v31
	ds_write2st64_b64 v210, v[190:191], v[192:193] offset1:4
	v_cvt_pk_bf16_f32 v212, v60, v61
	v_cvt_pk_bf16_f32 v213, v62, v63
	v_cvt_pk_bf16_f32 v214, v44, v45
	v_cvt_pk_bf16_f32 v215, v46, v47
	ds_write2st64_b64 v210, v[212:213], v[214:215] offset0:8 offset1:12
	s_waitcnt lgkmcnt(0)
	ds_read_b64_tr_b16 v[0:1], v151 offset:0
	ds_read_b64_tr_b16 v[2:3], v199 offset:0
	ds_read_b64_tr_b16 v[28:29], v151 offset:1024
	ds_read_b64_tr_b16 v[30:31], v199 offset:1024
	ds_read_b64_tr_b16 v[24:25], v151 offset:2048
	ds_read_b64_tr_b16 v[26:27], v199 offset:2048
	ds_read_b64_tr_b16 v[20:21], v151 offset:3072
	ds_read_b64_tr_b16 v[22:23], v199 offset:3072
	ds_read_b64_tr_b16 v[16:17], v151 offset:4096
	ds_read_b64_tr_b16 v[18:19], v199 offset:4096
	ds_read_b64_tr_b16 v[44:45], v151 offset:5120
	ds_read_b64_tr_b16 v[46:47], v199 offset:5120
	ds_read_b64_tr_b16 v[40:41], v151 offset:6144
	ds_read_b64_tr_b16 v[42:43], v199 offset:6144
	ds_read_b64_tr_b16 v[52:53], v151 offset:7168
	ds_read_b64_tr_b16 v[54:55], v199 offset:7168
	s_waitcnt lgkmcnt(0)
	s_nop 0
	v_mfma_f32_32x32x16_bf16 v[0:15], v[68:71], v[0:3], 0
	v_mfma_f32_32x32x16_bf16 v[0:15], v[64:67], v[28:31], v[0:15]
	v_mfma_f32_32x32x16_bf16 v[0:15], v[76:79], v[24:27], v[0:15]
	v_mfma_f32_32x32x16_bf16 v[0:15], v[72:75], v[20:23], v[0:15]
	v_mfma_f32_32x32x16_bf16 v[0:15], v[84:87], v[16:19], v[0:15]
	v_mfma_f32_32x32x16_bf16 v[0:15], v[80:83], v[44:47], v[0:15]
	v_mfma_f32_32x32x16_bf16 v[0:15], v[92:95], v[40:43], v[0:15]
	v_mfma_f32_32x32x16_bf16 v[0:15], v[88:91], v[52:55], v[0:15]
	s_and_saveexec_b64 s[2:3], s[68:69]
	s_cbranch_execz .LBB0_198
	s_nop 7
	v_add_u32_e32 v16, v200, v146
	v_add_u32_e32 v16, 0x2000, v16
	ds_read2_b64 v[16:19], v16 offset1:2
	s_waitcnt lgkmcnt(0)
	v_lshlrev_b32_e32 v10, 16, v19
	v_and_b32_e32 v11, 0xffff0000, v19
	v_pk_fma_f32 v[6:7], v[102:103], v[10:11], v[6:7]
	s_nop 0
	v_mul_f32_e32 v10, v7, v7
	v_fmaak_f32 v10, v240, v10, 0xc0135761
	v_mul_f32_e32 v11, v6, v6
	v_mul_f32_e32 v10, v7, v10
	v_fmaak_f32 v11, v240, v11, 0xc0135761
	v_mul_f32_e32 v11, v6, v11
	v_exp_f32_e32 v10, v10
	v_exp_f32_e32 v11, v11
	v_add_f32_e32 v8, 1.0, v10
	v_rcp_f32_e32 v9, v8
	v_add_f32_e32 v8, 1.0, v11
	v_lshlrev_b32_e32 v10, 16, v18
	v_and_b32_e32 v11, 0xffff0000, v18
	v_pk_fma_f32 v[4:5], v[100:101], v[10:11], v[4:5]
	v_and_b32_e32 v13, 0xffff0000, v17
	v_mul_f32_e32 v10, v5, v5
	v_fmaak_f32 v10, v240, v10, 0xc0135761
	v_mul_f32_e32 v11, v4, v4
	v_mul_f32_e32 v10, v5, v10
	v_fmaak_f32 v11, v240, v11, 0xc0135761
	v_mul_f32_e32 v11, v4, v11
	v_exp_f32_e32 v10, v10
	v_exp_f32_e32 v12, v11
	v_and_b32_e32 v15, 0xffff0000, v16
	v_add_f32_e32 v10, 1.0, v10
	v_rcp_f32_e32 v11, v10
	v_add_f32_e32 v10, 1.0, v12
	v_lshlrev_b32_e32 v12, 16, v17
	v_pk_fma_f32 v[2:3], v[98:99], v[12:13], v[2:3]
	v_rcp_f32_e32 v8, v8
	v_mul_f32_e32 v12, v3, v3
	v_fmaak_f32 v12, v240, v12, 0xc0135761
	v_mul_f32_e32 v13, v2, v2
	v_mul_f32_e32 v12, v3, v12
	v_fmaak_f32 v13, v240, v13, 0xc0135761
	v_mul_f32_e32 v13, v2, v13
	v_exp_f32_e32 v12, v12
	v_exp_f32_e32 v14, v13
	s_cmp_eq_u32 s24, -2
	v_add_f32_e32 v12, 1.0, v12
	v_rcp_f32_e32 v13, v12
	v_add_f32_e32 v12, 1.0, v14
	v_lshlrev_b32_e32 v14, 16, v16
	v_pk_fma_f32 v[0:1], v[96:97], v[14:15], v[0:1]
	v_rcp_f32_e32 v12, v12
	v_mul_f32_e32 v14, v1, v1
	v_fmaak_f32 v14, v240, v14, 0xc0135761
	v_mul_f32_e32 v15, v0, v0
	v_mul_f32_e32 v14, v1, v14
	v_fmaak_f32 v15, v240, v15, 0xc0135761
	v_mul_f32_e32 v15, v0, v15
	v_exp_f32_e32 v14, v14
	v_exp_f32_e32 v16, v15
	v_rcp_f32_e32 v10, v10
	v_add_f32_e32 v14, 1.0, v14
	v_rcp_f32_e32 v15, v14
	v_add_f32_e32 v14, 1.0, v16
	v_rcp_f32_e32 v14, v14
	s_cselect_b64 vcc, -1, 0
	s_ashr_i32 s53, s52, 31
	v_pk_mul_f32 v[6:7], v[6:7], v[8:9]
	v_lshl_add_u64 v[8:9], s[52:53], 4, v[120:121]
	v_cndmask_b32_e64 v9, v9, 0, vcc
	v_cndmask_b32_e32 v8, v8, v154, vcc
	v_pk_mul_f32 v[2:3], v[2:3], v[12:13]
	v_pk_mul_f32 v[0:1], v[0:1], v[14:15]
	v_lshlrev_b64 v[8:9], 11, v[8:9]
	v_pk_mul_f32 v[4:5], v[4:5], v[10:11]
	v_lshl_add_u64 v[8:9], v[126:127], 0, v[8:9]
	v_cvt_pk_bf16_f32 v0, v0, v1
	v_cvt_pk_bf16_f32 v1, v2, v3
	v_cvt_pk_bf16_f32 v2, v4, v5
	v_cvt_pk_bf16_f32 v3, v6, v7
	global_store_dwordx2 v[8:9], v[0:1], off
	global_store_dwordx2 v[8:9], v[2:3], off offset:16

.LBB0_199:
	s_waitcnt vmcnt(9)
	v_mfma_f32_32x32x16_bf16 v[0:15], v[112:115], v[128:131], 0
	v_mfma_f32_32x32x16_bf16 v[16:31], v[112:115], v[132:135], 0
	v_mfma_f32_32x32x16_bf16 v[48:63], v[112:115], v[136:139], 0
	v_mfma_f32_32x32x16_bf16 v[32:47], v[112:115], v[140:143], 0
	ds_write_b128 v148, v[112:115] offset:8192
	s_cmp_gt_i32 s24, -3
	s_cselect_b64 s[2:3], -1, 0
	s_or_b64 s[52:53], s[2:3], s[50:51]
	s_nop 7
	v_fmac_f32_e32 v0, v172, v186
	v_fmac_f32_e32 v16, v174, v188
	v_fmac_f32_e32 v48, v172, v187
	v_fmac_f32_e32 v32, v174, v189
	v_fmac_f32_e32 v0, v241, v187
	v_fmac_f32_e32 v16, v242, v189
	v_fmac_f32_e32 v48, v173, v186
	v_fmac_f32_e32 v32, v175, v188
	v_fmac_f32_e32 v1, v172, v0
	v_fmac_f32_e32 v17, v174, v16
	v_fmac_f32_e32 v49, v172, v48
	v_fmac_f32_e32 v33, v174, v32
	v_fmac_f32_e32 v1, v241, v48
	v_fmac_f32_e32 v17, v242, v32
	v_fmac_f32_e32 v49, v173, v0
	v_fmac_f32_e32 v33, v175, v16
	v_fmac_f32_e32 v2, v172, v1
	v_fmac_f32_e32 v18, v174, v17
	v_fmac_f32_e32 v50, v172, v49
	v_fmac_f32_e32 v34, v174, v33
	v_fmac_f32_e32 v2, v241, v49
	v_fmac_f32_e32 v18, v242, v33
	v_fmac_f32_e32 v50, v173, v1
	v_fmac_f32_e32 v34, v175, v17
	v_fmac_f32_e32 v3, v172, v2
	v_fmac_f32_e32 v19, v174, v18
	v_fmac_f32_e32 v51, v172, v50
	v_fmac_f32_e32 v35, v174, v34
	v_fmac_f32_e32 v3, v241, v50
	v_fmac_f32_e32 v19, v242, v34
	v_fmac_f32_e32 v51, v173, v2
	v_fmac_f32_e32 v35, v175, v18
	v_cvt_pk_bf16_f32 v190, v0, v1
	v_cvt_pk_bf16_f32 v191, v2, v3
	v_cvt_pk_bf16_f32 v192, v16, v17
	v_cvt_pk_bf16_f32 v193, v18, v19
	ds_write2st64_b64 v207, v[190:191], v[192:193] offset1:4
	v_cvt_pk_bf16_f32 v212, v48, v49
	v_cvt_pk_bf16_f32 v213, v50, v51
	v_cvt_pk_bf16_f32 v214, v32, v33
	v_cvt_pk_bf16_f32 v215, v34, v35
	ds_write2st64_b64 v207, v[212:213], v[214:215] offset0:8 offset1:12
	v_fmac_f32_e32 v4, v172, v3
	v_fmac_f32_e32 v20, v174, v19
	v_fmac_f32_e32 v52, v172, v51
	v_fmac_f32_e32 v36, v174, v35
	v_fmac_f32_e32 v4, v241, v51
	v_fmac_f32_e32 v20, v242, v35
	v_fmac_f32_e32 v52, v173, v3
	v_fmac_f32_e32 v36, v175, v19
	v_fmac_f32_e32 v5, v172, v4
	v_fmac_f32_e32 v21, v174, v20
	v_fmac_f32_e32 v53, v172, v52
	v_fmac_f32_e32 v37, v174, v36
	v_fmac_f32_e32 v5, v241, v52
	v_fmac_f32_e32 v21, v242, v36
	v_fmac_f32_e32 v53, v173, v4
	v_fmac_f32_e32 v37, v175, v20
	v_fmac_f32_e32 v6, v172, v5
	v_fmac_f32_e32 v22, v174, v21
	v_fmac_f32_e32 v54, v172, v53
	v_fmac_f32_e32 v38, v174, v37
	v_fmac_f32_e32 v6, v241, v53
	v_fmac_f32_e32 v22, v242, v37
	v_fmac_f32_e32 v54, v173, v5
	v_fmac_f32_e32 v38, v175, v21
	v_fmac_f32_e32 v7, v172, v6
	v_fmac_f32_e32 v23, v174, v22
	v_fmac_f32_e32 v55, v172, v54
	v_fmac_f32_e32 v39, v174, v38
	v_fmac_f32_e32 v7, v241, v54
	v_fmac_f32_e32 v23, v242, v38
	v_fmac_f32_e32 v55, v173, v6
	v_fmac_f32_e32 v39, v175, v22
	v_cvt_pk_bf16_f32 v190, v4, v5
	v_cvt_pk_bf16_f32 v191, v6, v7
	v_cvt_pk_bf16_f32 v192, v20, v21
	v_cvt_pk_bf16_f32 v193, v22, v23
	ds_write2st64_b64 v208, v[190:191], v[192:193] offset1:4
	v_cvt_pk_bf16_f32 v212, v52, v53
	v_cvt_pk_bf16_f32 v213, v54, v55
	v_cvt_pk_bf16_f32 v214, v36, v37
	v_cvt_pk_bf16_f32 v215, v38, v39
	ds_write2st64_b64 v208, v[212:213], v[214:215] offset0:8 offset1:12
	v_fmac_f32_e32 v8, v172, v7
	v_fmac_f32_e32 v24, v174, v23
	v_fmac_f32_e32 v56, v172, v55
	v_fmac_f32_e32 v40, v174, v39
	v_fmac_f32_e32 v8, v241, v55
	v_fmac_f32_e32 v24, v242, v39
	v_fmac_f32_e32 v56, v173, v7
	v_fmac_f32_e32 v40, v175, v23
	v_fmac_f32_e32 v9, v172, v8
	v_fmac_f32_e32 v25, v174, v24
	v_fmac_f32_e32 v57, v172, v56
	v_fmac_f32_e32 v41, v174, v40
	v_fmac_f32_e32 v9, v241, v56
	v_fmac_f32_e32 v25, v242, v40
	v_fmac_f32_e32 v57, v173, v8
	v_fmac_f32_e32 v41, v175, v24
	v_fmac_f32_e32 v10, v172, v9
	v_fmac_f32_e32 v26, v174, v25
	v_fmac_f32_e32 v58, v172, v57
	v_fmac_f32_e32 v42, v174, v41
	v_fmac_f32_e32 v10, v241, v57
	v_fmac_f32_e32 v26, v242, v41
	v_fmac_f32_e32 v58, v173, v9
	v_fmac_f32_e32 v42, v175, v25
	v_fmac_f32_e32 v11, v172, v10
	v_fmac_f32_e32 v27, v174, v26
	v_fmac_f32_e32 v59, v172, v58
	v_fmac_f32_e32 v43, v174, v42
	v_fmac_f32_e32 v11, v241, v58
	v_fmac_f32_e32 v27, v242, v42
	v_fmac_f32_e32 v59, v173, v10
	v_fmac_f32_e32 v43, v175, v26
	v_cvt_pk_bf16_f32 v190, v8, v9
	v_cvt_pk_bf16_f32 v191, v10, v11
	v_cvt_pk_bf16_f32 v192, v24, v25
	v_cvt_pk_bf16_f32 v193, v26, v27
	ds_write2st64_b64 v209, v[190:191], v[192:193] offset1:4
	v_cvt_pk_bf16_f32 v212, v56, v57
	v_cvt_pk_bf16_f32 v213, v58, v59
	v_cvt_pk_bf16_f32 v214, v40, v41
	v_cvt_pk_bf16_f32 v215, v42, v43
	ds_write2st64_b64 v209, v[212:213], v[214:215] offset0:8 offset1:12
	v_fmac_f32_e32 v12, v172, v11
	v_fmac_f32_e32 v28, v174, v27
	v_fmac_f32_e32 v60, v172, v59
	v_fmac_f32_e32 v44, v174, v43
	v_fmac_f32_e32 v12, v241, v59
	v_fmac_f32_e32 v28, v242, v43
	v_fmac_f32_e32 v60, v173, v11
	v_fmac_f32_e32 v44, v175, v27
	v_fmac_f32_e32 v13, v172, v12
	v_fmac_f32_e32 v29, v174, v28
	v_fmac_f32_e32 v61, v172, v60
	v_fmac_f32_e32 v45, v174, v44
	v_fmac_f32_e32 v13, v241, v60
	v_fmac_f32_e32 v29, v242, v44
	v_fmac_f32_e32 v61, v173, v12
	v_fmac_f32_e32 v45, v175, v28
	v_fmac_f32_e32 v14, v172, v13
	v_fmac_f32_e32 v30, v174, v29
	v_fmac_f32_e32 v62, v172, v61
	v_fmac_f32_e32 v46, v174, v45
	v_fmac_f32_e32 v14, v241, v61
	v_fmac_f32_e32 v30, v242, v45
	v_fmac_f32_e32 v62, v173, v13
	v_fmac_f32_e32 v46, v175, v29
	v_fmac_f32_e32 v15, v172, v14
	v_fmac_f32_e32 v31, v174, v30
	v_fmac_f32_e32 v63, v172, v62
	v_fmac_f32_e32 v47, v174, v46
	v_fmac_f32_e32 v15, v241, v62
	v_fmac_f32_e32 v31, v242, v46
	v_fmac_f32_e32 v63, v173, v14
	v_fmac_f32_e32 v47, v175, v30
	v_mov_b32_e32 v186, v15
	v_mov_b32_e32 v187, v63
	v_mov_b32_e32 v188, v31
	v_mov_b32_e32 v189, v47
	v_cvt_pk_bf16_f32 v190, v12, v13
	v_cvt_pk_bf16_f32 v191, v14, v15
	v_cvt_pk_bf16_f32 v192, v28, v29
	v_cvt_pk_bf16_f32 v193, v30, v31
	ds_write2st64_b64 v210, v[190:191], v[192:193] offset1:4
	v_cvt_pk_bf16_f32 v212, v60, v61
	v_cvt_pk_bf16_f32 v213, v62, v63
	v_cvt_pk_bf16_f32 v214, v44, v45
	v_cvt_pk_bf16_f32 v215, v46, v47
	ds_write2st64_b64 v210, v[212:213], v[214:215] offset0:8 offset1:12
	s_waitcnt lgkmcnt(0)
	ds_read_b64_tr_b16 v[0:1], v151 offset:0
	ds_read_b64_tr_b16 v[2:3], v199 offset:0
	ds_read_b64_tr_b16 v[28:29], v151 offset:1024
	ds_read_b64_tr_b16 v[30:31], v199 offset:1024
	ds_read_b64_tr_b16 v[24:25], v151 offset:2048
	ds_read_b64_tr_b16 v[26:27], v199 offset:2048
	ds_read_b64_tr_b16 v[20:21], v151 offset:3072
	ds_read_b64_tr_b16 v[22:23], v199 offset:3072
	ds_read_b64_tr_b16 v[16:17], v151 offset:4096
	ds_read_b64_tr_b16 v[18:19], v199 offset:4096
	ds_read_b64_tr_b16 v[44:45], v151 offset:5120
	ds_read_b64_tr_b16 v[46:47], v199 offset:5120
	ds_read_b64_tr_b16 v[40:41], v151 offset:6144
	ds_read_b64_tr_b16 v[42:43], v199 offset:6144
	ds_read_b64_tr_b16 v[52:53], v151 offset:7168
	ds_read_b64_tr_b16 v[54:55], v199 offset:7168
	s_waitcnt lgkmcnt(0)
	s_nop 0
	v_mfma_f32_32x32x16_bf16 v[0:15], v[68:71], v[0:3], 0
	v_mfma_f32_32x32x16_bf16 v[0:15], v[64:67], v[28:31], v[0:15]
	v_mfma_f32_32x32x16_bf16 v[0:15], v[76:79], v[24:27], v[0:15]
	v_mfma_f32_32x32x16_bf16 v[0:15], v[72:75], v[20:23], v[0:15]
	v_mfma_f32_32x32x16_bf16 v[0:15], v[84:87], v[16:19], v[0:15]
	v_mfma_f32_32x32x16_bf16 v[0:15], v[80:83], v[44:47], v[0:15]
	v_mfma_f32_32x32x16_bf16 v[0:15], v[92:95], v[40:43], v[0:15]
	v_mfma_f32_32x32x16_bf16 v[0:15], v[88:91], v[52:55], v[0:15]
	s_and_saveexec_b64 s[2:3], s[52:53]
	s_cbranch_execz .LBB0_186
	s_nop 7
	v_add_u32_e32 v16, v200, v146
	v_add_u32_e32 v16, 0x2000, v16
	ds_read2_b64 v[16:19], v16 offset1:2
	s_waitcnt lgkmcnt(0)
	v_lshlrev_b32_e32 v10, 16, v19
	v_and_b32_e32 v11, 0xffff0000, v19
	v_pk_fma_f32 v[6:7], v[102:103], v[10:11], v[6:7]
	s_nop 0
	v_mul_f32_e32 v10, v7, v7
	v_fmaak_f32 v10, v240, v10, 0xc0135761
	v_mul_f32_e32 v11, v6, v6
	v_mul_f32_e32 v10, v7, v10
	v_fmaak_f32 v11, v240, v11, 0xc0135761
	v_mul_f32_e32 v11, v6, v11
	v_exp_f32_e32 v10, v10
	v_exp_f32_e32 v11, v11
	v_add_f32_e32 v8, 1.0, v10
	v_rcp_f32_e32 v9, v8
	v_add_f32_e32 v8, 1.0, v11
	v_lshlrev_b32_e32 v10, 16, v18
	v_and_b32_e32 v11, 0xffff0000, v18
	v_pk_fma_f32 v[4:5], v[100:101], v[10:11], v[4:5]
	v_and_b32_e32 v13, 0xffff0000, v17
	v_mul_f32_e32 v10, v5, v5
	v_fmaak_f32 v10, v240, v10, 0xc0135761
	v_mul_f32_e32 v11, v4, v4
	v_mul_f32_e32 v10, v5, v10
	v_fmaak_f32 v11, v240, v11, 0xc0135761
	v_mul_f32_e32 v11, v4, v11
	v_exp_f32_e32 v10, v10
	v_exp_f32_e32 v12, v11
	v_and_b32_e32 v15, 0xffff0000, v16
	v_add_f32_e32 v10, 1.0, v10
	v_rcp_f32_e32 v11, v10
	v_add_f32_e32 v10, 1.0, v12
	v_lshlrev_b32_e32 v12, 16, v17
	v_pk_fma_f32 v[2:3], v[98:99], v[12:13], v[2:3]
	v_rcp_f32_e32 v8, v8
	v_mul_f32_e32 v12, v3, v3
	v_fmaak_f32 v12, v240, v12, 0xc0135761
	v_mul_f32_e32 v13, v2, v2
	v_mul_f32_e32 v12, v3, v12
	v_fmaak_f32 v13, v240, v13, 0xc0135761
	v_mul_f32_e32 v13, v2, v13
	v_exp_f32_e32 v12, v12
	v_exp_f32_e32 v14, v13
	s_cmp_eq_u32 s24, -3
	v_add_f32_e32 v12, 1.0, v12
	v_rcp_f32_e32 v13, v12
	v_add_f32_e32 v12, 1.0, v14
	v_lshlrev_b32_e32 v14, 16, v16
	v_pk_fma_f32 v[0:1], v[96:97], v[14:15], v[0:1]
	v_rcp_f32_e32 v12, v12
	v_mul_f32_e32 v14, v1, v1
	v_fmaak_f32 v14, v240, v14, 0xc0135761
	v_mul_f32_e32 v15, v0, v0
	v_mul_f32_e32 v14, v1, v14
	v_fmaak_f32 v15, v240, v15, 0xc0135761
	v_mul_f32_e32 v15, v0, v15
	v_exp_f32_e32 v14, v14
	v_exp_f32_e32 v16, v15
	v_rcp_f32_e32 v10, v10
	v_add_f32_e32 v14, 1.0, v14
	v_rcp_f32_e32 v15, v14
	v_add_f32_e32 v14, 1.0, v16
	v_rcp_f32_e32 v14, v14
	s_cselect_b64 vcc, -1, 0
	s_ashr_i32 s15, s14, 31
	v_pk_mul_f32 v[6:7], v[6:7], v[8:9]
	v_lshl_add_u64 v[8:9], s[14:15], 4, v[120:121]
	v_cndmask_b32_e64 v9, v9, 0, vcc
	v_cndmask_b32_e32 v8, v8, v154, vcc
	v_pk_mul_f32 v[2:3], v[2:3], v[12:13]
	v_pk_mul_f32 v[0:1], v[0:1], v[14:15]
	v_lshlrev_b64 v[8:9], 11, v[8:9]
	v_pk_mul_f32 v[4:5], v[4:5], v[10:11]
	v_lshl_add_u64 v[8:9], v[126:127], 0, v[8:9]
	v_cvt_pk_bf16_f32 v0, v0, v1
	v_cvt_pk_bf16_f32 v1, v2, v3
	v_cvt_pk_bf16_f32 v2, v4, v5
	v_cvt_pk_bf16_f32 v3, v6, v7
	global_store_dwordx2 v[8:9], v[0:1], off
	global_store_dwordx2 v[8:9], v[2:3], off offset:16
	s_branch .LBB0_186
